# P3 start: abs-max butterfly via DPP/permlane swaps (exact max), on p3c
# speedup vs baseline: 1.0010x; 1.0009x over previous
; __device__ __forceinline__ float qk_bound(const float* q_g, const float* k_g, int lane) {
;     float gq = fabsf(q_g[lane]), gk = fabsf(k_g[lane]);
; #pragma unroll
;     for (int o = 1; o < 64; o <<= 1) { gq = fmaxf(gq, __shfl_xor(gq, o)); gk = fmaxf(gk, __shfl_xor(gk, o)); }
;     return attn_body::C2 * 64.0f * 1.02f * gq * gk;
; }
.LBB0_337:
	s_or_b64 exec, exec, s[4:5]
	s_mov_b64 s[4:5], s[0:1]
	s_waitcnt lgkmcnt(0)
	s_barrier
	v_mov_b32_e32 v2, v0
	s_mov_b32 s3, s2
	s_load_dwordx4 s[8:11], s[4:5], 0x38
	s_load_dwordx2 s[6:7], s[4:5], 0x70
	s_load_dword s3, s[24:25], 0x0
	v_and_b32_e32 v2, 63, v2
	v_lshlrev_b32_e32 v2, 2, v2
	v_or_b32_e32 v8, 0xfffffe00, v0
	s_waitcnt lgkmcnt(0)
	s_add_u32 s86, s6, 0x1c000000
	s_addc_u32 s87, s7, 0
	s_mov_b32 s4, s3
	global_load_dword v3, v2, s[8:9]
	global_load_dword v4, v2, s[10:11]
	s_mov_b64 s[4:5], 0x1c100000
	s_mov_b64 s[8:9], 0x800
	v_lshlrev_b32_e32 v20, 2, v0
	v_mov_b32_e32 v21, 0
	v_lshl_add_u64 v[20:21], s[6:7], 0, v[20:21]
	v_lshl_add_u64 v[20:21], v[20:21], 0, s[4:5]
	global_load_dword v22, v[20:21], off
	global_load_dword v23, v[20:21], off offset:2048
	v_lshlrev_b32_e32 v9, 2, v0
	v_add_u32_e32 v9, 0x18800, v9
	s_waitcnt vmcnt(2)
	v_max_f32_e64 v3, |v3|, |v3|
	v_max_f32_e64 v4, |v4|, |v4|
	s_nop 1
	v_max_f32_dpp v24, v3, v3 quad_perm:[1,0,3,2] row_mask:0xf bank_mask:0xf
	v_max_f32_dpp v25, v4, v4 quad_perm:[1,0,3,2] row_mask:0xf bank_mask:0xf
	s_nop 0
	v_max_f32_dpp v3, v24, v24 quad_perm:[2,3,0,1] row_mask:0xf bank_mask:0xf
	v_max_f32_dpp v4, v25, v25 quad_perm:[2,3,0,1] row_mask:0xf bank_mask:0xf
	s_nop 0
	v_max_f32_dpp v24, v3, v3 row_half_mirror row_mask:0xf bank_mask:0xf
	v_max_f32_dpp v25, v4, v4 row_half_mirror row_mask:0xf bank_mask:0xf
	s_nop 0
	v_max_f32_dpp v3, v24, v24 row_mirror row_mask:0xf bank_mask:0xf
	v_max_f32_dpp v4, v25, v25 row_mirror row_mask:0xf bank_mask:0xf
	v_mov_b32_e32 v24, v3
	v_mov_b32_e32 v25, v4
	s_nop 1
	v_permlane16_swap_b32_e32 v24, v3
	v_permlane16_swap_b32_e32 v25, v4
	v_max_f32_e32 v5, v24, v3
	v_max_f32_e32 v4, v25, v4
	v_mov_b32_e32 v7, v5
	v_mov_b32_e32 v6, v4
	s_nop 1
	v_permlane32_swap_b32_e32 v5, v7
	v_permlane32_swap_b32_e32 v4, v6
	s_waitcnt vmcnt(0)
	ds_write_b32 v9, v22
	ds_write_b32 v9, v23 offset:2048
	s_cmp_lg_u32 0, -1
	s_cselect_b32 s4, 0, 0
	s_addk_i32 s4, 0x6000
	s_add_i32 s8, 0, 0x14800
	s_add_u32 s14, s6, 0x43800
	s_addc_u32 s15, s7, 0
	s_add_u32 s47, s6, 0x6000000
	s_addc_u32 s48, s7, 0
	s_add_u32 s49, s6, 0x8000000
	s_addc_u32 s50, s7, 0
	s_waitcnt lgkmcnt(2)
	v_max_f32_e32 v7, v7, v7
	v_max_f32_e32 v5, v5, v5
	s_add_u32 s51, s6, 0xa000000
	v_lshlrev_b32_e32 v3, 1, v0
	v_and_b32_e32 v205, 31, v0
	v_bfe_u32 v198, v0, 5, 1
	v_lshlrev_b32_e32 v10, 4, v0
	v_max_f32_e32 v5, v5, v7
	s_waitcnt lgkmcnt(1)
	v_max_f32_e32 v6, v6, v6
	v_max_f32_e32 v4, v4, v4
	s_addc_u32 s52, s7, 0
	v_mov_b32_e32 v201, 0
	v_and_b32_e32 v3, 32, v3
	v_and_b32_e32 v11, 0xc0, v10
	v_lshlrev_b32_e32 v12, 10, v198
	v_lshlrev_b32_e32 v13, 4, v205
	v_bfe_u32 v233, v0, 3, 3
	v_max_f32_e32 v4, v4, v6
	v_mul_f32_e32 v5, 0x413c5bb7, v5
	s_add_u32 s53, s6, 0xc000000
	v_and_b32_e32 v8, 24, v170
	v_add_u32_e32 v9, s4, v3
	v_add_u32_e32 v3, 0, v3
	v_lshlrev_b32_e32 v10, 9, v205
	v_add3_u32 v207, 0, v12, v13
	v_lshlrev_b32_e32 v13, 4, v198
	v_lshlrev_b32_e32 v202, 5, v0
	v_lshlrev_b32_e32 v15, 6, v0
	v_or_b32_e32 v17, 8, v233
	v_or_b32_e32 v19, 16, v233
	v_or_b32_e32 v20, 24, v233
	v_mul_f32_e32 v237, v5, v4
	v_lshl_or_b32 v4, v198, 8, v11
	v_mov_b32_e32 v203, v201
	s_addc_u32 s54, s7, 0
	v_lshlrev_b32_e32 v2, 9, v1
	v_lshl_or_b32 v10, v198, 3, v10
	v_lshlrev_b32_e32 v232, 2, v198
	v_lshlrev_b32_e32 v12, 10, v233
	v_lshlrev_b32_e32 v14, 10, v17
	v_lshlrev_b32_e32 v16, 10, v19
	v_lshlrev_b32_e32 v18, 10, v20
	v_add3_u32 v238, v9, v8, v4
	v_add3_u32 v239, v3, v8, v4
	v_add_u32_e32 v240, s8, v13
	v_and_b32_e32 v4, 0xe00, v15
	v_lshl_add_u64 v[6:7], s[6:7], 0, v[202:203]
	s_mov_b64 s[8:9], 0x1c000000
	s_add_u32 s55, s6, 0x2000000
	v_add_u32_e32 v3, 0, v13
	s_mov_b32 s28, 0xffff0000
	s_mov_b32 s13, 0
	s_movk_i32 s33, 0x6000
	v_and_b32_e32 v204, 56, v170
	v_cmp_gt_u32_e64 s[4:5], 32, v1
	v_lshlrev_b32_e32 v206, 3, v1
	v_or_b32_e32 v241, 0xc0, v232
	v_or_b32_e32 v253, 0xf3, v232
	v_or_b32_e32 v236, 0xf8, v232
	v_or_b32_e32 v244, 0xf9, v232
	v_or_b32_e32 v245, 0xfa, v232
	v_or_b32_e32 v246, 0xfb, v232
	v_lshlrev_b32_e32 v247, 9, v198
	v_lshlrev_b32_e32 v248, 7, v233
	v_lshlrev_b32_e32 v249, 7, v17
	v_lshlrev_b32_e32 v250, 7, v19
	v_lshlrev_b32_e32 v251, 7, v20
	s_movk_i32 s46, 0x84
	v_lshl_add_u64 v[208:209], v[6:7], 0, s[8:9]
	s_addc_u32 s56, s7, 0
	v_mov_b32_e32 v199, v198
	v_add_u32_e32 v203, 0x14a00, v3
	v_add_u32_e32 v254, 0x14900, v3
	v_lshlrev_b32_e32 v210, 4, v1
	v_mov_b32_e32 v211, v201
	v_mov_b32_e32 v213, s2
	v_lshlrev_b32_e32 v234, 1, v2
	v_lshlrev_b32_e32 v214, 1, v8
	s_mov_b64 s[16:17], 0x10000
	s_movk_i32 s57, 0x2000
	v_lshlrev_b32_e32 v255, 1, v10
	s_mov_b64 s[20:21], 0x20000
	s_movk_i32 s58, 0x4000
	s_mov_b64 s[22:23], 0x30000
	s_mov_b64 s[26:27], 0x50000
	s_mov_b32 s29, -1
	v_lshlrev_b32_e32 v216, 1, v4
	v_lshlrev_b32_e32 v218, 1, v12
	v_lshlrev_b32_e32 v220, 1, v14
	v_lshlrev_b32_e32 v222, 1, v16
	v_lshlrev_b32_e32 v224, 1, v18
	s_mov_b64 s[30:31], 0x1000
	s_mov_b32 s59, 0xe000000
	s_brev_b32 s60, 8
	s_brev_b32 s61, 64
	s_mov_b32 s62, 0x2001000
	s_mov_b64 s[34:35], 0x1000000
	s_mov_b64 s[36:37], 0xe00400
	s_mov_b64 s[38:39], 0xe00000
	v_mov_b32_e32 v252, 0xff800000
	s_branch .LBB0_343
